# in-proj A parked stores trickled two per iteration (after S1 and S3 loads) in the last three K-loop iterations, history-based vmcnt
# speedup vs baseline: 1.0037x; 1.0037x over previous
; #define PG8_STAGE(bufoff, gbase, voff) do { _Pragma("unroll") for (int _i = 0; _i < 2; ++_i) \
;         __builtin_amdgcn_global_load_lds((const unsigned*)((const char*)(gbase) + (voff)[_i]), (PG8_LAS unsigned*)(lds + (bufoff) + ldsw + _i * 8192), 16, 0, 0); } while (0)
; #define PG8_LDA(dst, b, h) do { _Pragma("unroll") for (int m = 0; m < 4; ++m) _Pragma("unroll") for (int k = 0; k < 2; ++k) dst[m][k] = *(const PG8_LAS bf16x8*)(lds + PG8_SA(b, h) + aoff + m * 2048 + k * 1024); } while (0)
; #define PG8_LDB(dst, b, h) do { _Pragma("unroll") for (int n = 0; n < 2; ++n) _Pragma("unroll") for (int k = 0; k < 2; ++k) dst[n][k] = *(const PG8_LAS bf16x8*)(lds + PG8_SB(b, h) + boff + n * 2048 + k * 1024); } while (0)
; #define PG8_SCHED __builtin_amdgcn_sched_barrier(0)
;     ...
;         for (int t = 0; t < nt; t += 2) {
;             const bool last = (t == nt - 2);
;             const char* a1 = cA + (size_t)(t + 1) * kstep;
;             const char* a2 = last ? nA : cA + (size_t)(t + 2) * kstep; const char* b2 = last ? nB : cB + (size_t)(t + 2) * kstep;
;             const char* a3 = a2 + kstep; const char* b3 = b2 + kstep;
;             PG8_LDB(B0, 0, 0); PG8_LDB(B1, 0, 1); PG8_SCHED; PG8_LDA(At, 0, 0); PG8_STAGE(PG8_SA(1, 1), a1 + hstep, voffA);
.Lpka_nomove:
	s_mov_b32 s100, 0
.LBB0_206:
	s_add_u32 s72, s38, 0xfffc0080
	s_addc_u32 s73, s39, -1
	s_add_i32 s82, 0, 0x10000
	s_cmp_eq_u32 s81, 12
	s_cselect_b32 s77, s2, s73
	s_cselect_b32 s76, s31, s72
	s_cselect_b32 s73, s29, s80
	s_cselect_b32 s72, s60, s61
	s_add_i32 s86, 0, 0x14000
	s_waitcnt lgkmcnt(0)
	v_add_u32_e32 v156, s82, v195
	v_add_u32_e32 v183, s86, v195
	ds_read_b128 v[144:147], v156
	ds_read_b128 v[148:151], v156 offset:1024
	ds_read_b128 v[152:155], v156 offset:2048
	ds_read_b128 v[156:159], v156 offset:3072
	ds_read_b128 v[186:189], v183
	ds_read_b128 v[198:201], v183 offset:1024
	ds_read_b128 v[202:205], v183 offset:2048
	ds_read_b128 v[206:209], v183 offset:3072
	v_lshl_add_u64 v[242:243], s[38:39], 0, v[178:179]
	s_add_i32 m0, s63, 0xc000
	ds_read_b128 v[210:213], v197
	ds_read_b128 v[214:217], v197 offset:1024
	ds_read_b128 v[218:221], v197 offset:2048
	ds_read_b128 v[222:225], v197 offset:3072
	ds_read_b128 v[226:229], v197 offset:4096
	ds_read_b128 v[230:233], v197 offset:5120
	ds_read_b128 v[234:237], v197 offset:6144
	ds_read_b128 v[238:241], v197 offset:7168
	global_load_lds_dwordx4 v[242:243], off
	v_lshl_add_u64 v[242:243], s[38:39], 0, v[180:181]
	s_add_i32 m0, s63, 0xe000
	s_nop 0
	global_load_lds_dwordx4 v[242:243], off
	s_lshl_b32 s100, s100, 1
	s_and_b32 s100, s100, 6
	s_cmp_eq_u32 s101, 0
	s_cbranch_scc1 .Lpka_na
	s_cmp_lt_i32 s81, 8
	s_cbranch_scc1 .Lpka_na
	s_or_b32 s100, s100, 1
	s_cmp_eq_u32 s101, 6
	s_cbranch_scc1 .Lpka_s0a
	s_cmp_eq_u32 s101, 5
	s_cbranch_scc1 .Lpka_s1a
	s_cmp_eq_u32 s101, 4
	s_cbranch_scc1 .Lpka_s2a
	s_cmp_eq_u32 s101, 3
	s_cbranch_scc1 .Lpka_s3a
	s_cmp_eq_u32 s101, 2
	s_cbranch_scc1 .Lpka_s4a
	global_store_dwordx4 v[254:255], v[12:15], off offset:64
	s_branch .Lpka_ia

; #define PG8_STAGE(bufoff, gbase, voff) do { _Pragma("unroll") for (int _i = 0; _i < 2; ++_i) \
;         __builtin_amdgcn_global_load_lds((const unsigned*)((const char*)(gbase) + (voff)[_i]), (PG8_LAS unsigned*)(lds + (bufoff) + ldsw + _i * 8192), 16, 0, 0); } while (0)
; #define PG8_LDA(dst, b, h) do { _Pragma("unroll") for (int m = 0; m < 4; ++m) _Pragma("unroll") for (int k = 0; k < 2; ++k) dst[m][k] = *(const PG8_LAS bf16x8*)(lds + PG8_SA(b, h) + aoff + m * 2048 + k * 1024); } while (0)
; #define PG8_LDB(dst, b, h) do { _Pragma("unroll") for (int n = 0; n < 2; ++n) _Pragma("unroll") for (int k = 0; k < 2; ++k) dst[n][k] = *(const PG8_LAS bf16x8*)(lds + PG8_SB(b, h) + boff + n * 2048 + k * 1024); } while (0)
; #define PG8_WAIT_V(n) asm volatile("s_waitcnt vmcnt(" #n ")" ::: "memory")
; #define PG8_WAIT_L(n) asm volatile("s_waitcnt lgkmcnt(" #n ")" ::: "memory")
; #define PG8_BAR __builtin_amdgcn_s_barrier()
; #define PG8_SCHED __builtin_amdgcn_sched_barrier(0)
;     ...
;             PG8_LDB(B0, 0, 0); PG8_LDB(B1, 0, 1); PG8_SCHED; PG8_LDA(At, 0, 0); PG8_STAGE(PG8_SA(1, 1), a1 + hstep, voffA);
;             PG8_WAIT_V(8); PG8_WAIT_L(0); PG8_BAR; PG8_MMA(0, 0, At, B0); PG8_MMA(0, 1, At, B1); PG8_BAR; PG8_SCHED;
.Lpka_ia:
	s_sub_u32 s101, s101, 1
.Lpka_na:
	s_bcnt1_i32_b32 vcc_lo, s100
	s_cmp_eq_u32 vcc_lo, 0
	s_cbranch_scc1 .Lpka_w8a
	s_cmp_eq_u32 vcc_lo, 1
	s_cbranch_scc1 .Lpka_w9a
	s_waitcnt vmcnt(10)
	s_branch .Lpka_da

; #define PG8_STAGE(bufoff, gbase, voff) do { _Pragma("unroll") for (int _i = 0; _i < 2; ++_i) \
;         __builtin_amdgcn_global_load_lds((const unsigned*)((const char*)(gbase) + (voff)[_i]), (PG8_LAS unsigned*)(lds + (bufoff) + ldsw + _i * 8192), 16, 0, 0); } while (0)
; #define PG8_LDA(dst, b, h) do { _Pragma("unroll") for (int m = 0; m < 4; ++m) _Pragma("unroll") for (int k = 0; k < 2; ++k) dst[m][k] = *(const PG8_LAS bf16x8*)(lds + PG8_SA(b, h) + aoff + m * 2048 + k * 1024); } while (0)
; #define PG8_WAIT_V(n) asm volatile("s_waitcnt vmcnt(" #n ")" ::: "memory")
; #define PG8_WAIT_L(n) asm volatile("s_waitcnt lgkmcnt(" #n ")" ::: "memory")
; #define PG8_BAR __builtin_amdgcn_s_barrier()
; #define PG8_SCHED __builtin_amdgcn_sched_barrier(0)
;     ...
;             PG8_WAIT_V(8); PG8_WAIT_L(0); PG8_BAR; PG8_MMA(0, 0, At, B0); PG8_MMA(0, 1, At, B1); PG8_BAR; PG8_SCHED;
;             PG8_LDA(At, 0, 1); PG8_STAGE(PG8_SB(0, 0), b2, voffB); PG8_STAGE(PG8_SB(0, 1), b2 + hstepB, voffB); PG8_STAGE(PG8_SA(0, 0), a2, voffA);
.Lpka_da:
	s_waitcnt lgkmcnt(0)
	s_barrier
	s_setprio 1
	s_waitcnt lgkmcnt(0)
	v_mfma_f32_16x16x32_bf16 v[132:135], v[144:147], v[210:213], v[132:135]
	v_mfma_f32_16x16x32_bf16 v[128:131], v[152:155], v[210:213], v[128:131]
	v_mfma_f32_16x16x32_bf16 v[116:119], v[144:147], v[218:221], v[116:119]
	v_mfma_f32_16x16x32_bf16 v[112:115], v[152:155], v[218:221], v[112:115]
	v_mfma_f32_16x16x32_bf16 v[100:103], v[144:147], v[226:229], v[100:103]
	v_mfma_f32_16x16x32_bf16 v[96:99], v[152:155], v[226:229], v[96:99]
	v_mfma_f32_16x16x32_bf16 v[84:87], v[144:147], v[234:237], v[84:87]
	v_mfma_f32_16x16x32_bf16 v[80:83], v[152:155], v[234:237], v[80:83]
	v_mfma_f32_16x16x32_bf16 v[132:135], v[148:151], v[214:217], v[132:135]
	v_mfma_f32_16x16x32_bf16 v[128:131], v[156:159], v[214:217], v[128:131]
	v_mfma_f32_16x16x32_bf16 v[116:119], v[148:151], v[222:225], v[116:119]
	v_mfma_f32_16x16x32_bf16 v[112:115], v[156:159], v[222:225], v[112:115]
	v_mfma_f32_16x16x32_bf16 v[100:103], v[148:151], v[230:233], v[100:103]
	v_mfma_f32_16x16x32_bf16 v[96:99], v[156:159], v[230:233], v[96:99]
	v_mfma_f32_16x16x32_bf16 v[84:87], v[148:151], v[238:241], v[84:87]
	v_mfma_f32_16x16x32_bf16 v[80:83], v[156:159], v[238:241], v[80:83]
	s_setprio 0
	s_setprio 1
	v_mfma_f32_16x16x32_bf16 v[140:143], v[186:189], v[210:213], v[140:143]
	v_mfma_f32_16x16x32_bf16 v[136:139], v[202:205], v[210:213], v[136:139]
	v_mfma_f32_16x16x32_bf16 v[124:127], v[186:189], v[218:221], v[124:127]
	v_mfma_f32_16x16x32_bf16 v[120:123], v[202:205], v[218:221], v[120:123]
	v_mfma_f32_16x16x32_bf16 v[108:111], v[186:189], v[226:229], v[108:111]
	v_mfma_f32_16x16x32_bf16 v[104:107], v[202:205], v[226:229], v[104:107]
	v_mfma_f32_16x16x32_bf16 v[92:95], v[186:189], v[234:237], v[92:95]
	v_mfma_f32_16x16x32_bf16 v[88:91], v[202:205], v[234:237], v[88:91]
	v_mfma_f32_16x16x32_bf16 v[140:143], v[198:201], v[214:217], v[140:143]
	v_mfma_f32_16x16x32_bf16 v[136:139], v[206:209], v[214:217], v[136:139]
	v_mfma_f32_16x16x32_bf16 v[124:127], v[198:201], v[222:225], v[124:127]
	v_mfma_f32_16x16x32_bf16 v[120:123], v[206:209], v[222:225], v[120:123]
	v_mfma_f32_16x16x32_bf16 v[108:111], v[198:201], v[230:233], v[108:111]
	v_mfma_f32_16x16x32_bf16 v[104:107], v[206:209], v[230:233], v[104:107]
	v_mfma_f32_16x16x32_bf16 v[92:95], v[198:201], v[238:241], v[92:95]
	v_mfma_f32_16x16x32_bf16 v[88:91], v[206:209], v[238:241], v[88:91]
	s_setprio 0
	s_barrier
	s_add_i32 s82, s82, s15
	v_lshl_add_u64 v[242:243], s[72:73], 0, v[170:171]
	s_mov_b32 m0, s82
	ds_read_b128 v[210:213], v197 offset:16384
	ds_read_b128 v[214:217], v197 offset:17408
	ds_read_b128 v[218:221], v197 offset:18432
	ds_read_b128 v[222:225], v197 offset:19456
	ds_read_b128 v[226:229], v197 offset:20480
	ds_read_b128 v[230:233], v197 offset:21504
	ds_read_b128 v[234:237], v197 offset:22528
	ds_read_b128 v[238:241], v197 offset:23552
	global_load_lds_dwordx4 v[242:243], off
	s_add_i32 m0, s82, 0x2000
	s_add_u32 s82, s72, 0x10000
	v_lshl_add_u64 v[244:245], s[72:73], 0, v[166:167]
	s_addc_u32 s83, s73, 0
	s_add_i32 s86, s86, s15
	global_load_lds_dwordx4 v[244:245], off
	v_lshl_add_u64 v[246:247], s[82:83], 0, v[170:171]
	s_mov_b32 m0, s86
	v_lshl_add_u64 v[248:249], s[76:77], 0, v[168:169]
	global_load_lds_dwordx4 v[246:247], off
	v_lshl_add_u64 v[246:247], s[82:83], 0, v[166:167]
	s_add_i32 m0, s86, 0x2000
	s_nop 0
	global_load_lds_dwordx4 v[246:247], off
	v_lshl_add_u64 v[246:247], s[76:77], 0, v[172:173]
	s_mov_b32 m0, s63
	s_nop 0
	global_load_lds_dwordx4 v[246:247], off
	s_mov_b32 m0, s64
	s_nop 0
	global_load_lds_dwordx4 v[248:249], off
	s_lshl_b32 s100, s100, 1
	s_and_b32 s100, s100, 6
	s_bcnt1_i32_b32 vcc_lo, s100
	s_cmp_eq_u32 vcc_lo, 0
	s_cbranch_scc1 .Lpka_w8b
	s_cmp_eq_u32 vcc_lo, 1
	s_cbranch_scc1 .Lpka_w9b
	s_waitcnt vmcnt(10)
	s_branch .Lpka_db

; #define PG8_STAGE(bufoff, gbase, voff) do { _Pragma("unroll") for (int _i = 0; _i < 2; ++_i) \
;         __builtin_amdgcn_global_load_lds((const unsigned*)((const char*)(gbase) + (voff)[_i]), (PG8_LAS unsigned*)(lds + (bufoff) + ldsw + _i * 8192), 16, 0, 0); } while (0)
; #define PG8_LDA(dst, b, h) do { _Pragma("unroll") for (int m = 0; m < 4; ++m) _Pragma("unroll") for (int k = 0; k < 2; ++k) dst[m][k] = *(const PG8_LAS bf16x8*)(lds + PG8_SA(b, h) + aoff + m * 2048 + k * 1024); } while (0)
; #define PG8_LDB(dst, b, h) do { _Pragma("unroll") for (int n = 0; n < 2; ++n) _Pragma("unroll") for (int k = 0; k < 2; ++k) dst[n][k] = *(const PG8_LAS bf16x8*)(lds + PG8_SB(b, h) + boff + n * 2048 + k * 1024); } while (0)
; #define PG8_WAIT_V(n) asm volatile("s_waitcnt vmcnt(" #n ")" ::: "memory")
; #define PG8_WAIT_L(n) asm volatile("s_waitcnt lgkmcnt(" #n ")" ::: "memory")
; #define PG8_BAR __builtin_amdgcn_s_barrier()
; #define PG8_SCHED __builtin_amdgcn_sched_barrier(0)
;     ...
;             PG8_WAIT_V(8); PG8_WAIT_L(0); PG8_BAR; PG8_MMA(1, 0, At, B0); PG8_MMA(1, 1, At, B1); PG8_BAR; PG8_SCHED;
;             PG8_LDB(B0, 1, 0); PG8_LDB(B1, 1, 1); PG8_SCHED; PG8_LDA(At, 1, 0); PG8_STAGE(PG8_SA(0, 1), a2 + hstep, voffA);
.Lpka_db:
	s_waitcnt lgkmcnt(0)
	s_barrier
	s_setprio 1
	s_waitcnt lgkmcnt(0)
	v_mfma_f32_16x16x32_bf16 v[68:71], v[144:147], v[210:213], v[68:71]
	v_mfma_f32_16x16x32_bf16 v[64:67], v[152:155], v[210:213], v[64:67]
	v_mfma_f32_16x16x32_bf16 v[52:55], v[144:147], v[218:221], v[52:55]
	v_mfma_f32_16x16x32_bf16 v[48:51], v[152:155], v[218:221], v[48:51]
	v_mfma_f32_16x16x32_bf16 v[36:39], v[144:147], v[226:229], v[36:39]
	v_mfma_f32_16x16x32_bf16 v[32:35], v[152:155], v[226:229], v[32:35]
	v_mfma_f32_16x16x32_bf16 v[20:23], v[144:147], v[234:237], v[20:23]
	v_mfma_f32_16x16x32_bf16 v[16:19], v[152:155], v[234:237], v[16:19]
	v_mfma_f32_16x16x32_bf16 v[68:71], v[148:151], v[214:217], v[68:71]
	v_mfma_f32_16x16x32_bf16 v[64:67], v[156:159], v[214:217], v[64:67]
	v_mfma_f32_16x16x32_bf16 v[52:55], v[148:151], v[222:225], v[52:55]
	v_mfma_f32_16x16x32_bf16 v[48:51], v[156:159], v[222:225], v[48:51]
	v_mfma_f32_16x16x32_bf16 v[36:39], v[148:151], v[230:233], v[36:39]
	v_mfma_f32_16x16x32_bf16 v[32:35], v[156:159], v[230:233], v[32:35]
	v_mfma_f32_16x16x32_bf16 v[20:23], v[148:151], v[238:241], v[20:23]
	v_mfma_f32_16x16x32_bf16 v[16:19], v[156:159], v[238:241], v[16:19]
	s_setprio 0
	s_setprio 1
	v_mfma_f32_16x16x32_bf16 v[76:79], v[186:189], v[210:213], v[76:79]
	v_mfma_f32_16x16x32_bf16 v[72:75], v[202:205], v[210:213], v[72:75]
	v_mfma_f32_16x16x32_bf16 v[60:63], v[186:189], v[218:221], v[60:63]
	v_mfma_f32_16x16x32_bf16 v[56:59], v[202:205], v[218:221], v[56:59]
	v_mfma_f32_16x16x32_bf16 v[44:47], v[186:189], v[226:229], v[44:47]
	v_mfma_f32_16x16x32_bf16 v[40:43], v[202:205], v[226:229], v[40:43]
	v_mfma_f32_16x16x32_bf16 v[24:27], v[186:189], v[234:237], v[24:27]
	v_mfma_f32_16x16x32_bf16 v[28:31], v[202:205], v[234:237], v[28:31]
	v_mfma_f32_16x16x32_bf16 v[76:79], v[198:201], v[214:217], v[76:79]
	v_mfma_f32_16x16x32_bf16 v[72:75], v[206:209], v[214:217], v[72:75]
	v_mfma_f32_16x16x32_bf16 v[60:63], v[198:201], v[222:225], v[60:63]
	v_mfma_f32_16x16x32_bf16 v[56:59], v[206:209], v[222:225], v[56:59]
	v_mfma_f32_16x16x32_bf16 v[44:47], v[198:201], v[230:233], v[44:47]
	v_mfma_f32_16x16x32_bf16 v[40:43], v[206:209], v[230:233], v[40:43]
	v_mfma_f32_16x16x32_bf16 v[24:27], v[198:201], v[238:241], v[24:27]
	v_mfma_f32_16x16x32_bf16 v[28:31], v[206:209], v[238:241], v[28:31]
	s_setprio 0
	s_barrier
	s_add_i32 s82, 0, 0x18000
	s_add_i32 s83, 0, 0x1c000
	v_add_u32_e32 v156, s82, v195
	v_add_u32_e32 v183, s83, v195
	ds_read_b128 v[144:147], v156
	ds_read_b128 v[148:151], v156 offset:1024
	ds_read_b128 v[152:155], v156 offset:2048
	ds_read_b128 v[156:159], v156 offset:3072
	ds_read_b128 v[186:189], v183
	ds_read_b128 v[198:201], v183 offset:1024
	ds_read_b128 v[202:205], v183 offset:2048
	ds_read_b128 v[206:209], v183 offset:3072
	s_add_u32 s76, s76, 0x40000
	s_addc_u32 s77, s77, 0
	s_mov_b32 m0, s65
	v_lshl_add_u64 v[250:251], s[76:77], 0, v[172:173]
	ds_read_b128 v[210:213], v197 offset:32768
	ds_read_b128 v[214:217], v197 offset:33792
	ds_read_b128 v[218:221], v197 offset:34816
	ds_read_b128 v[222:225], v197 offset:35840
	ds_read_b128 v[226:229], v197 offset:36864
	ds_read_b128 v[230:233], v197 offset:37888
	ds_read_b128 v[234:237], v197 offset:38912
	ds_read_b128 v[238:241], v197 offset:39936
	global_load_lds_dwordx4 v[250:251], off
	v_lshl_add_u64 v[250:251], s[76:77], 0, v[168:169]
	s_mov_b32 m0, s66
	s_nop 0
	global_load_lds_dwordx4 v[250:251], off
	s_lshl_b32 s100, s100, 1
	s_and_b32 s100, s100, 6
	s_cmp_eq_u32 s101, 0
	s_cbranch_scc1 .Lpka_nc
	s_cmp_lt_i32 s81, 8
	s_cbranch_scc1 .Lpka_nc
	s_or_b32 s100, s100, 1
	s_cmp_eq_u32 s101, 6
	s_cbranch_scc1 .Lpka_s0c
	s_cmp_eq_u32 s101, 5
	s_cbranch_scc1 .Lpka_s1c
	s_cmp_eq_u32 s101, 4
	s_cbranch_scc1 .Lpka_s2c
	s_cmp_eq_u32 s101, 3
	s_cbranch_scc1 .Lpka_s3c
	s_cmp_eq_u32 s101, 2
	s_cbranch_scc1 .Lpka_s4c
	global_store_dwordx4 v[254:255], v[12:15], off offset:64
	s_branch .Lpka_ic

; #define PG8_STAGE(bufoff, gbase, voff) do { _Pragma("unroll") for (int _i = 0; _i < 2; ++_i) \
;         __builtin_amdgcn_global_load_lds((const unsigned*)((const char*)(gbase) + (voff)[_i]), (PG8_LAS unsigned*)(lds + (bufoff) + ldsw + _i * 8192), 16, 0, 0); } while (0)
; #define PG8_LDA(dst, b, h) do { _Pragma("unroll") for (int m = 0; m < 4; ++m) _Pragma("unroll") for (int k = 0; k < 2; ++k) dst[m][k] = *(const PG8_LAS bf16x8*)(lds + PG8_SA(b, h) + aoff + m * 2048 + k * 1024); } while (0)
; #define PG8_WAIT_V(n) asm volatile("s_waitcnt vmcnt(" #n ")" ::: "memory")
; #define PG8_WAIT_L(n) asm volatile("s_waitcnt lgkmcnt(" #n ")" ::: "memory")
; #define PG8_BAR __builtin_amdgcn_s_barrier()
; #define PG8_SCHED __builtin_amdgcn_sched_barrier(0)
;     ...
;             PG8_WAIT_V(8); PG8_WAIT_L(0); PG8_BAR; PG8_MMA(0, 0, At, B0); PG8_MMA(0, 1, At, B1); PG8_BAR; PG8_SCHED;
;             PG8_LDA(At, 1, 1); PG8_STAGE(PG8_SB(1, 0), b3, voffB); PG8_STAGE(PG8_SB(1, 1), b3 + hstepB, voffB); PG8_STAGE(PG8_SA(1, 0), a3, voffA);
.Lpka_dc:
	s_waitcnt lgkmcnt(0)
	s_barrier
	s_setprio 1
	s_waitcnt lgkmcnt(0)
	v_mfma_f32_16x16x32_bf16 v[132:135], v[144:147], v[210:213], v[132:135]
	v_mfma_f32_16x16x32_bf16 v[128:131], v[152:155], v[210:213], v[128:131]
	v_mfma_f32_16x16x32_bf16 v[116:119], v[144:147], v[218:221], v[116:119]
	v_mfma_f32_16x16x32_bf16 v[112:115], v[152:155], v[218:221], v[112:115]
	v_mfma_f32_16x16x32_bf16 v[100:103], v[144:147], v[226:229], v[100:103]
	v_mfma_f32_16x16x32_bf16 v[96:99], v[152:155], v[226:229], v[96:99]
	v_mfma_f32_16x16x32_bf16 v[84:87], v[144:147], v[234:237], v[84:87]
	v_mfma_f32_16x16x32_bf16 v[80:83], v[152:155], v[234:237], v[80:83]
	v_mfma_f32_16x16x32_bf16 v[132:135], v[148:151], v[214:217], v[132:135]
	v_mfma_f32_16x16x32_bf16 v[128:131], v[156:159], v[214:217], v[128:131]
	v_mfma_f32_16x16x32_bf16 v[116:119], v[148:151], v[222:225], v[116:119]
	v_mfma_f32_16x16x32_bf16 v[112:115], v[156:159], v[222:225], v[112:115]
	v_mfma_f32_16x16x32_bf16 v[100:103], v[148:151], v[230:233], v[100:103]
	v_mfma_f32_16x16x32_bf16 v[96:99], v[156:159], v[230:233], v[96:99]
	v_mfma_f32_16x16x32_bf16 v[84:87], v[148:151], v[238:241], v[84:87]
	v_mfma_f32_16x16x32_bf16 v[80:83], v[156:159], v[238:241], v[80:83]
	s_setprio 0
	s_setprio 1
	v_mfma_f32_16x16x32_bf16 v[140:143], v[186:189], v[210:213], v[140:143]
	v_mfma_f32_16x16x32_bf16 v[136:139], v[202:205], v[210:213], v[136:139]
	v_mfma_f32_16x16x32_bf16 v[124:127], v[186:189], v[218:221], v[124:127]
	v_mfma_f32_16x16x32_bf16 v[120:123], v[202:205], v[218:221], v[120:123]
	v_mfma_f32_16x16x32_bf16 v[108:111], v[186:189], v[226:229], v[108:111]
	v_mfma_f32_16x16x32_bf16 v[104:107], v[202:205], v[226:229], v[104:107]
	v_mfma_f32_16x16x32_bf16 v[92:95], v[186:189], v[234:237], v[92:95]
	v_mfma_f32_16x16x32_bf16 v[88:91], v[202:205], v[234:237], v[88:91]
	v_mfma_f32_16x16x32_bf16 v[140:143], v[198:201], v[214:217], v[140:143]
	v_mfma_f32_16x16x32_bf16 v[136:139], v[206:209], v[214:217], v[136:139]
	v_mfma_f32_16x16x32_bf16 v[124:127], v[198:201], v[222:225], v[124:127]
	v_mfma_f32_16x16x32_bf16 v[120:123], v[206:209], v[222:225], v[120:123]
	v_mfma_f32_16x16x32_bf16 v[108:111], v[198:201], v[230:233], v[108:111]
	v_mfma_f32_16x16x32_bf16 v[104:107], v[206:209], v[230:233], v[104:107]
	v_mfma_f32_16x16x32_bf16 v[92:95], v[198:201], v[238:241], v[92:95]
	v_mfma_f32_16x16x32_bf16 v[88:91], v[206:209], v[238:241], v[88:91]
	s_setprio 0
	s_barrier
	s_add_i32 s76, s82, s15
	v_lshl_add_u64 v[242:243], v[242:243], 0, s[4:5]
	s_mov_b32 m0, s76
	ds_read_b128 v[210:213], v197 offset:49152
	ds_read_b128 v[214:217], v197 offset:50176
	ds_read_b128 v[218:221], v197 offset:51200
	ds_read_b128 v[222:225], v197 offset:52224
	ds_read_b128 v[226:229], v197 offset:53248
	ds_read_b128 v[230:233], v197 offset:54272
	ds_read_b128 v[234:237], v197 offset:55296
	ds_read_b128 v[238:241], v197 offset:56320
	global_load_lds_dwordx4 v[242:243], off
	s_add_i32 m0, s76, 0x2000
	s_add_u32 s72, s72, 0x10080
	v_lshl_add_u64 v[242:243], v[244:245], 0, s[4:5]
	s_addc_u32 s73, s73, 0
	s_add_i32 s76, s83, s15
	global_load_lds_dwordx4 v[242:243], off
	v_lshl_add_u64 v[242:243], s[72:73], 0, v[170:171]
	s_mov_b32 m0, s76
	s_nop 0
	global_load_lds_dwordx4 v[242:243], off
	v_lshl_add_u64 v[242:243], s[72:73], 0, v[166:167]
	s_add_i32 m0, s76, 0x2000
	s_nop 0
	global_load_lds_dwordx4 v[242:243], off
	v_lshl_add_u64 v[242:243], v[246:247], 0, s[4:5]
	s_mov_b32 m0, s74
	s_nop 0
	global_load_lds_dwordx4 v[242:243], off
	v_lshl_add_u64 v[242:243], v[248:249], 0, s[4:5]
	s_mov_b32 m0, s75
	s_nop 0
	global_load_lds_dwordx4 v[242:243], off
	s_lshl_b32 s100, s100, 1
	s_and_b32 s100, s100, 6
	s_bcnt1_i32_b32 vcc_lo, s100
	s_cmp_eq_u32 vcc_lo, 0
	s_cbranch_scc1 .Lpka_w8e
	s_cmp_eq_u32 vcc_lo, 1
	s_cbranch_scc1 .Lpka_w9e
	s_waitcnt vmcnt(10)
	s_branch .Lpka_de

; #define PG8_WAIT_V(n) asm volatile("s_waitcnt vmcnt(" #n ")" ::: "memory")
; #define PG8_WAIT_L(n) asm volatile("s_waitcnt lgkmcnt(" #n ")" ::: "memory")
; #define PG8_BAR __builtin_amdgcn_s_barrier()
; #define PG8_SCHED __builtin_amdgcn_sched_barrier(0)
;     ...
;             PG8_WAIT_V(8); PG8_WAIT_L(0); PG8_BAR; PG8_MMA(1, 0, At, B0); PG8_MMA(1, 1, At, B1); PG8_BAR; PG8_SCHED;
;         }
;         if constexpr (ALIGN_EPI) { if (wr == 0) PG8_BAR; }
.Lpka_de:
	s_waitcnt lgkmcnt(0)
	s_barrier
	s_setprio 1
	s_waitcnt lgkmcnt(0)
	v_mfma_f32_16x16x32_bf16 v[68:71], v[144:147], v[210:213], v[68:71]
	v_mfma_f32_16x16x32_bf16 v[64:67], v[152:155], v[210:213], v[64:67]
	v_mfma_f32_16x16x32_bf16 v[52:55], v[144:147], v[218:221], v[52:55]
	v_mfma_f32_16x16x32_bf16 v[48:51], v[152:155], v[218:221], v[48:51]
	v_mfma_f32_16x16x32_bf16 v[36:39], v[144:147], v[226:229], v[36:39]
	v_mfma_f32_16x16x32_bf16 v[32:35], v[152:155], v[226:229], v[32:35]
	v_mfma_f32_16x16x32_bf16 v[20:23], v[144:147], v[234:237], v[20:23]
	v_mfma_f32_16x16x32_bf16 v[16:19], v[152:155], v[234:237], v[16:19]
	v_mfma_f32_16x16x32_bf16 v[68:71], v[148:151], v[214:217], v[68:71]
	v_mfma_f32_16x16x32_bf16 v[64:67], v[156:159], v[214:217], v[64:67]
	v_mfma_f32_16x16x32_bf16 v[52:55], v[148:151], v[222:225], v[52:55]
	v_mfma_f32_16x16x32_bf16 v[48:51], v[156:159], v[222:225], v[48:51]
	v_mfma_f32_16x16x32_bf16 v[36:39], v[148:151], v[230:233], v[36:39]
	v_mfma_f32_16x16x32_bf16 v[32:35], v[156:159], v[230:233], v[32:35]
	v_mfma_f32_16x16x32_bf16 v[20:23], v[148:151], v[238:241], v[20:23]
	v_mfma_f32_16x16x32_bf16 v[16:19], v[156:159], v[238:241], v[16:19]
	s_setprio 0
	s_setprio 1
	v_mfma_f32_16x16x32_bf16 v[76:79], v[186:189], v[210:213], v[76:79]
	v_mfma_f32_16x16x32_bf16 v[72:75], v[202:205], v[210:213], v[72:75]
	v_mfma_f32_16x16x32_bf16 v[60:63], v[186:189], v[218:221], v[60:63]
	v_mfma_f32_16x16x32_bf16 v[56:59], v[202:205], v[218:221], v[56:59]
	v_mfma_f32_16x16x32_bf16 v[44:47], v[186:189], v[226:229], v[44:47]
	v_mfma_f32_16x16x32_bf16 v[40:43], v[202:205], v[226:229], v[40:43]
	v_mfma_f32_16x16x32_bf16 v[24:27], v[186:189], v[234:237], v[24:27]
	v_mfma_f32_16x16x32_bf16 v[28:31], v[202:205], v[234:237], v[28:31]
	v_mfma_f32_16x16x32_bf16 v[76:79], v[198:201], v[214:217], v[76:79]
	v_mfma_f32_16x16x32_bf16 v[72:75], v[206:209], v[214:217], v[72:75]
	v_mfma_f32_16x16x32_bf16 v[60:63], v[198:201], v[222:225], v[60:63]
	v_mfma_f32_16x16x32_bf16 v[56:59], v[206:209], v[222:225], v[56:59]
	v_mfma_f32_16x16x32_bf16 v[44:47], v[198:201], v[230:233], v[44:47]
	v_mfma_f32_16x16x32_bf16 v[40:43], v[206:209], v[230:233], v[40:43]
	v_mfma_f32_16x16x32_bf16 v[24:27], v[198:201], v[238:241], v[24:27]
	v_mfma_f32_16x16x32_bf16 v[28:31], v[206:209], v[238:241], v[28:31]
	s_setprio 0
	s_barrier
	s_add_i32 s81, s81, 2
	s_add_u32 s38, s38, 0x100
	s_addc_u32 s39, s39, 0
	s_add_u32 s61, s61, 0x100
	s_addc_u32 s80, s80, 0
	s_cmp_gt_u32 s81, 13
	s_cbranch_scc0 .LBB0_206
	v_mov_b32_e32 v162, 0x500
	v_mov_b32_e32 v163, 0
	v_mov_b32_e32 v164, 0x4ff
	v_mov_b32_e32 v165, 0
	v_mov_b32_e32 v190, 0x358637bd
	v_mov_b32_e32 v191, 1
	v_mov_b32_e32 v192, 0x300
	v_mov_b32_e32 v193, 0x200
	s_and_b64 vcc, exec, s[22:23]
	s_cbranch_vccz .LBB0_209
	s_barrier
